# baseline (speedup 1.0000x reference)
; __device__ __forceinline__ void phase_norm(const float* xin, const float* g, const float* mod, int shift_off, int scale_off, bf16_t* hout) {
;     ...
;     for (int row = blockIdx.x * 8 + wid; row < NTOK; row += nw) {
;         const int b = row >> 13;
;         const float* xr = xin + (size_t)row * DM;
;         f32x4 v[8]; float ss = 0.f;
; #pragma unroll
;         for (int i = 0; i < 8; ++i) { v[i] = *(const f32x4*)(xr + i * 256 + lane * 4); ss += v[i][0] * v[i][0] + v[i][1] * v[i][1] + v[i][2] * v[i][2] + v[i][3] * v[i][3]; }
;         ss = wave_sum(ss);
;         const float rstd = rsqrtf(ss * (1.0f / DM) + 1e-6f);
;         const float* mb = mod + (size_t)b * 6 * DM;
; #pragma unroll
;         for (int i = 0; i < 8; ++i) {
;             const int col = i * 256 + lane * 4;
;             const f32x4 g4 = *(const f32x4*)(g + col), sc4 = *(const f32x4*)(mb + scale_off + col), sh4 = *(const f32x4*)(mb + shift_off + col);
.LBB0_54:
	s_mov_b64 s[14:15], s[0:1]
	v_mov_b32_e32 v0, v166
	s_nop 0
	v_ashrrev_i32_e32 v1, 6, v0
	v_add_u32_e32 v34, s70, v1
	v_cmp_gt_i32_e32 vcc, s19, v34
	s_and_saveexec_b64 s[12:13], vcc
	s_cbranch_execz .LBB0_53
	v_lshlrev_b32_e32 v1, 2, v0
	v_cmp_lt_i32_e32 vcc, v169, v168
	v_and_b32_e32 v2, 0xfc, v1
	s_load_dwordx2 s[4:5], s[14:15], 0x80
	s_load_dwordx2 s[16:17], s[14:15], 0x0
	s_load_dwordx2 s[22:23], s[14:15], 0x20
	v_cndmask_b32_e32 v1, v167, v169, vcc
	v_cmp_lt_i32_e32 vcc, v170, v168
	v_lshlrev_b32_e32 v72, 2, v1
	v_ashrrev_i32_e32 v35, 31, v34
	v_cndmask_b32_e32 v1, v167, v170, vcc
	v_cmp_lt_i32_e32 vcc, v171, v168
	v_lshlrev_b32_e32 v73, 2, v1
	v_lshlrev_b64 v[18:19], 12, v[34:35]
	v_cndmask_b32_e32 v1, v167, v171, vcc
	v_cmp_lt_i32_e32 vcc, v172, v168
	v_lshlrev_b32_e32 v74, 2, v1
	v_and_b32_e32 v3, 63, v0
	v_cndmask_b32_e32 v1, v167, v172, vcc
	v_cmp_lt_i32_e32 vcc, v173, v168
	v_lshlrev_b32_e32 v75, 2, v1
	v_lshlrev_b32_e32 v32, 2, v2
	v_cndmask_b32_e32 v1, v167, v173, vcc
	v_cmp_lt_i32_e32 vcc, v174, v168
	v_lshlrev_b32_e32 v76, 2, v1
	v_or_b32_e32 v10, 0x400, v2
	v_cndmask_b32_e32 v1, v167, v174, vcc
	v_lshl_or_b32 v18, v3, 3, v18
	v_lshlrev_b32_e32 v77, 2, v1
	s_waitcnt lgkmcnt(0)
	v_lshl_add_u64 v[36:37], s[22:23], 0, v[32:33]
	v_lshlrev_b32_e32 v32, 2, v10
	v_or_b32_e32 v12, 0x500, v2
	v_lshl_add_u64 v[0:1], s[4:5], 0, v[18:19]
	v_lshl_add_u64 v[38:39], s[22:23], 0, v[32:33]
	v_lshlrev_b32_e32 v32, 2, v12
	v_or_b32_e32 v14, 0x600, v2
	v_lshl_add_u64 v[46:47], v[0:1], 0, s[6:7]
	v_lshlrev_b64 v[0:1], 13, v[34:35]
	v_lshl_add_u64 v[40:41], s[22:23], 0, v[32:33]
	v_lshlrev_b32_e32 v32, 2, v14
	v_or_b32_e32 v16, 0x700, v2
	v_lshl_or_b32 v0, v3, 4, v0
	s_add_u32 s14, s4, 0x6300000
	v_or_b32_e32 v4, 0x100, v2
	v_or_b32_e32 v6, 0x200, v2
	v_or_b32_e32 v8, 0x300, v2
	v_lshl_add_u64 v[42:43], s[22:23], 0, v[32:33]
	v_lshlrev_b32_e32 v32, 2, v16
	v_lshl_add_u64 v[0:1], s[16:17], 0, v[0:1]
	s_addc_u32 s15, s5, 0
	v_lshl_add_u64 v[44:45], s[22:23], 0, v[32:33]
	v_lshl_add_u64 v[48:49], v[0:1], 0, s[8:9]
	s_mov_b64 s[16:17], 0
	v_lshlrev_b32_e32 v32, 2, v2
	v_lshlrev_b32_e32 v50, 2, v4
	v_lshlrev_b32_e32 v52, 2, v6
	v_lshlrev_b32_e32 v54, 2, v8
	v_lshlrev_b32_e32 v56, 2, v10
	v_lshlrev_b32_e32 v58, 2, v12
	v_lshlrev_b32_e32 v60, 2, v14
	v_lshlrev_b32_e32 v62, 2, v16
	v_mov_b32_e32 v51, v33
	v_mov_b32_e32 v53, v33
	v_mov_b32_e32 v55, v33
	v_mov_b32_e32 v57, v33
	v_mov_b32_e32 v59, v33
	v_mov_b32_e32 v61, v33
	v_mov_b32_e32 v63, v33
	s_mov_b32 s98, -1
	global_load_dwordx4 v[24:27], v[48:49], off offset:-4096
	global_load_dwordx4 v[28:31], v[48:49], off offset:-3072
	global_load_dwordx4 v[20:23], v[48:49], off offset:-2048
	global_load_dwordx4 v[16:19], v[48:49], off offset:-1024
	global_load_dwordx4 v[12:15], v[48:49], off
	global_load_dwordx4 v[8:11], v[48:49], off offset:1024
	global_load_dwordx4 v[4:7], v[48:49], off offset:2048
	global_load_dwordx4 v[0:3], v[48:49], off offset:3072
	s_waitcnt vmcnt(0)
.LBB0_56:
	v_ashrrev_i32_e32 v35, 13, v34
	s_nop 0
	v_readfirstlane_b32 s99, v35
	s_cmp_eq_u32 s99, s98
	s_cbranch_scc1 .Lnorm1a_params_ok
	s_mov_b32 s98, s99
	v_mul_i32_i24_e32 v160, 6, v35
	v_ashrrev_i32_e32 v161, 31, v160
	v_lshlrev_b64 v[160:161], 13, v[160:161]
	v_lshl_add_u64 v[160:161], s[14:15], 0, v[160:161]
	v_lshl_add_u64 v[162:163], v[160:161], 0, s[10:11]
	v_lshl_add_u64 v[152:153], v[162:163], 0, v[32:33]
	v_lshl_add_u64 v[154:155], v[160:161], 0, v[32:33]
	v_lshl_add_u64 v[156:157], v[162:163], 0, v[56:57]
	v_lshl_add_u64 v[158:159], v[160:161], 0, v[56:57]
	global_load_dwordx4 v[112:115], v[36:37], off
	global_load_dwordx4 v[116:119], v[36:37], off offset:1024
	global_load_dwordx4 v[120:123], v[36:37], off offset:2048
	global_load_dwordx4 v[124:127], v[36:37], off offset:3072
	global_load_dwordx4 v[128:131], v[38:39], off
	global_load_dwordx4 v[132:135], v[38:39], off offset:1024
	global_load_dwordx4 v[136:139], v[38:39], off offset:2048
	global_load_dwordx4 v[140:143], v[38:39], off offset:3072
	global_load_dwordx4 v[176:179], v[152:153], off
	global_load_dwordx4 v[180:183], v[152:153], off offset:1024
	global_load_dwordx4 v[184:187], v[152:153], off offset:2048
	global_load_dwordx4 v[188:191], v[152:153], off offset:3072
	global_load_dwordx4 v[192:195], v[156:157], off
	global_load_dwordx4 v[196:199], v[156:157], off offset:1024
	global_load_dwordx4 v[200:203], v[156:157], off offset:2048
	global_load_dwordx4 v[204:207], v[156:157], off offset:3072
	global_load_dwordx4 v[208:211], v[154:155], off
	global_load_dwordx4 v[212:215], v[154:155], off offset:1024
	global_load_dwordx4 v[216:219], v[154:155], off offset:2048
	global_load_dwordx4 v[220:223], v[154:155], off offset:3072
	global_load_dwordx4 v[224:227], v[158:159], off
	global_load_dwordx4 v[228:231], v[158:159], off offset:1024
	global_load_dwordx4 v[144:147], v[158:159], off offset:2048
	global_load_dwordx4 v[148:151], v[158:159], off offset:3072
	s_waitcnt vmcnt(0)
.Lnorm1a_params_ok:
	v_add_u32_e32 v34, s48, v34
	v_lshl_add_u64 v[48:49], v[48:49], 0, s[52:53]
	v_cmp_lt_i32_e32 vcc, s21, v34
	s_mov_b64 s[100:101], vcc
	s_cbranch_vccnz .Lnorm1a_nopf
	global_load_dwordx4 v[78:81], v[48:49], off offset:-4096
	global_load_dwordx4 v[82:85], v[48:49], off offset:-3072
	global_load_dwordx4 v[86:89], v[48:49], off offset:-2048
	global_load_dwordx4 v[90:93], v[48:49], off offset:-1024
	global_load_dwordx4 v[94:97], v[48:49], off
	global_load_dwordx4 v[98:101], v[48:49], off offset:1024
	global_load_dwordx4 v[102:105], v[48:49], off offset:2048
	global_load_dwordx4 v[106:109], v[48:49], off offset:3072
	s_branch .Lnorm1a_pfdone
.Lnorm1a_nopf:
	s_waitcnt vmcnt(8)
; __device__ __forceinline__ unsigned cvt_pk_bf16(float lo, float hi) { unsigned r; asm volatile("v_cvt_pk_bf16_f32 %0, %1, %2" : "=v"(r) : "v"(lo), "v"(hi)); return r; }
; __device__ __forceinline__ void phase_norm(const float* xin, const float* g, const float* mod, int shift_off, int scale_off, bf16_t* hout) {
;     ...
;         for (int i = 0; i < 8; ++i) { v[i] = *(const f32x4*)(xr + i * 256 + lane * 4); ss += v[i][0] * v[i][0] + v[i][1] * v[i][1] + v[i][2] * v[i][2] + v[i][3] * v[i][3]; }
;         ss = wave_sum(ss);
;         const float rstd = rsqrtf(ss * (1.0f / DM) + 1e-6f);
;         const float* mb = mod + (size_t)b * 6 * DM;
; #pragma unroll
;         for (int i = 0; i < 8; ++i) {
;             const int col = i * 256 + lane * 4;
;             const f32x4 g4 = *(const f32x4*)(g + col), sc4 = *(const f32x4*)(mb + scale_off + col), sh4 = *(const f32x4*)(mb + shift_off + col);
;             f32x4 y = (v[i] * rstd) * g4; y = y * (sc4 + 1.0f) + sh4;
;             u32x2 w; w.x = cvt_pk_bf16(y[0], y[1]); w.y = cvt_pk_bf16(y[2], y[3]);
;             *(u32x2*)(hout + (size_t)row * DM + col) = w;
;         }
.Lnorm1a_pfdone:
	s_waitcnt vmcnt(23)
	v_mul_f32_e32 v35, v24, v24
	v_fmac_f32_e32 v35, v25, v25
	v_fmac_f32_e32 v35, v26, v26
	v_fmac_f32_e32 v35, v27, v27
	s_waitcnt vmcnt(22)
	v_mul_f32_e32 v175, v28, v28
	v_fmac_f32_e32 v175, v29, v29
	v_fmac_f32_e32 v175, v30, v30
	v_fmac_f32_e32 v175, v31, v31
	s_waitcnt vmcnt(21)
	v_fmac_f32_e32 v35, v20, v20
	v_fmac_f32_e32 v35, v21, v21
	v_fmac_f32_e32 v35, v22, v22
	v_fmac_f32_e32 v35, v23, v23
	s_waitcnt vmcnt(20)
	v_fmac_f32_e32 v175, v16, v16
	v_fmac_f32_e32 v175, v17, v17
	v_fmac_f32_e32 v175, v18, v18
	v_fmac_f32_e32 v175, v19, v19
	s_waitcnt vmcnt(19)
	v_fmac_f32_e32 v35, v12, v12
	v_fmac_f32_e32 v35, v13, v13
	v_fmac_f32_e32 v35, v14, v14
	v_fmac_f32_e32 v35, v15, v15
	s_waitcnt vmcnt(18)
	v_fmac_f32_e32 v175, v8, v8
	v_fmac_f32_e32 v175, v9, v9
	v_fmac_f32_e32 v175, v10, v10
	v_fmac_f32_e32 v175, v11, v11
	s_waitcnt vmcnt(17)
	v_fmac_f32_e32 v35, v4, v4
	v_fmac_f32_e32 v35, v5, v5
	v_fmac_f32_e32 v35, v6, v6
	v_fmac_f32_e32 v35, v7, v7
	s_waitcnt vmcnt(16)
	v_fmac_f32_e32 v175, v0, v0
	v_fmac_f32_e32 v175, v1, v1
	v_fmac_f32_e32 v175, v2, v2
	v_fmac_f32_e32 v175, v3, v3
	v_add_f32_e32 v35, v35, v175
	ds_bpermute_b32 v68, v72, v35
	s_waitcnt lgkmcnt(0)
	v_add_f32_e32 v35, v35, v68
	ds_bpermute_b32 v68, v73, v35
	s_waitcnt lgkmcnt(0)
	v_add_f32_e32 v35, v35, v68
	ds_bpermute_b32 v68, v74, v35
	s_waitcnt lgkmcnt(0)
	v_add_f32_e32 v35, v35, v68
	ds_bpermute_b32 v68, v75, v35
	s_waitcnt lgkmcnt(0)
	v_add_f32_e32 v35, v35, v68
	ds_bpermute_b32 v68, v76, v35
	s_waitcnt lgkmcnt(0)
	v_add_f32_e32 v35, v35, v68
	ds_bpermute_b32 v68, v77, v35
	s_waitcnt lgkmcnt(0)
	v_add_f32_e32 v35, v35, v68
	v_fmamk_f32 v35, v35, 0x3a000000, v69
	v_mul_f32_e32 v68, 0x4b800000, v35
	v_cmp_gt_f32_e32 vcc, s20, v35
	s_nop 1
	v_cndmask_b32_e32 v35, v35, v68, vcc
	v_rsq_f32_e32 v35, v35
	s_nop 0
	v_mul_f32_e32 v68, 0x45800000, v35
	v_cndmask_b32_e32 v68, v35, v68, vcc
	v_pk_mul_f32 v[24:25], v[24:25], v[68:69] op_sel_hi:[1,0]
	v_pk_mul_f32 v[26:27], v[26:27], v[68:69] op_sel_hi:[1,0]
	v_pk_mul_f32 v[24:25], v[112:113], v[24:25]
	v_pk_mul_f32 v[26:27], v[114:115], v[26:27]
	v_pk_add_f32 v[164:165], v[176:177], 1.0 op_sel_hi:[1,0]
	v_pk_add_f32 v[110:111], v[178:179], 1.0 op_sel_hi:[1,0]
	v_pk_fma_f32 v[24:25], v[164:165], v[24:25], v[208:209]
	v_pk_fma_f32 v[26:27], v[110:111], v[26:27], v[210:211]
	v_cvt_pk_bf16_f32 v24, v24, v25
	v_cvt_pk_bf16_f32 v25, v26, v27
	global_store_dwordx2 v[46:47], v[24:25], off
	v_pk_mul_f32 v[28:29], v[28:29], v[68:69] op_sel_hi:[1,0]
	v_pk_mul_f32 v[30:31], v[30:31], v[68:69] op_sel_hi:[1,0]
	v_pk_mul_f32 v[28:29], v[116:117], v[28:29]
	v_pk_mul_f32 v[30:31], v[118:119], v[30:31]
	v_pk_add_f32 v[164:165], v[180:181], 1.0 op_sel_hi:[1,0]
	v_pk_add_f32 v[110:111], v[182:183], 1.0 op_sel_hi:[1,0]
	v_pk_fma_f32 v[28:29], v[164:165], v[28:29], v[212:213]
	v_pk_fma_f32 v[30:31], v[110:111], v[30:31], v[214:215]
	v_cvt_pk_bf16_f32 v28, v28, v29
	v_cvt_pk_bf16_f32 v29, v30, v31
	global_store_dwordx2 v[46:47], v[28:29], off offset:512
	v_pk_mul_f32 v[20:21], v[20:21], v[68:69] op_sel_hi:[1,0]
	v_pk_mul_f32 v[22:23], v[22:23], v[68:69] op_sel_hi:[1,0]
	v_pk_mul_f32 v[20:21], v[120:121], v[20:21]
	v_pk_mul_f32 v[22:23], v[122:123], v[22:23]
	v_pk_add_f32 v[164:165], v[184:185], 1.0 op_sel_hi:[1,0]
	v_pk_add_f32 v[110:111], v[186:187], 1.0 op_sel_hi:[1,0]
	v_pk_fma_f32 v[20:21], v[164:165], v[20:21], v[216:217]
	v_pk_fma_f32 v[22:23], v[110:111], v[22:23], v[218:219]
	v_cvt_pk_bf16_f32 v20, v20, v21
	v_cvt_pk_bf16_f32 v21, v22, v23
	global_store_dwordx2 v[46:47], v[20:21], off offset:1024
	v_pk_mul_f32 v[16:17], v[16:17], v[68:69] op_sel_hi:[1,0]
	v_pk_mul_f32 v[18:19], v[18:19], v[68:69] op_sel_hi:[1,0]
	v_pk_mul_f32 v[16:17], v[124:125], v[16:17]
	v_pk_mul_f32 v[18:19], v[126:127], v[18:19]
	v_pk_add_f32 v[164:165], v[188:189], 1.0 op_sel_hi:[1,0]
	v_pk_add_f32 v[110:111], v[190:191], 1.0 op_sel_hi:[1,0]
	v_pk_fma_f32 v[16:17], v[164:165], v[16:17], v[220:221]
	v_pk_fma_f32 v[18:19], v[110:111], v[18:19], v[222:223]
	v_cvt_pk_bf16_f32 v16, v16, v17
	v_cvt_pk_bf16_f32 v17, v18, v19
	global_store_dwordx2 v[46:47], v[16:17], off offset:1536
	v_pk_mul_f32 v[12:13], v[12:13], v[68:69] op_sel_hi:[1,0]
	v_pk_mul_f32 v[14:15], v[14:15], v[68:69] op_sel_hi:[1,0]
	v_pk_mul_f32 v[12:13], v[128:129], v[12:13]
	v_pk_mul_f32 v[14:15], v[130:131], v[14:15]
	v_pk_add_f32 v[164:165], v[192:193], 1.0 op_sel_hi:[1,0]
	v_pk_add_f32 v[110:111], v[194:195], 1.0 op_sel_hi:[1,0]
	v_pk_fma_f32 v[12:13], v[164:165], v[12:13], v[224:225]
	v_pk_fma_f32 v[14:15], v[110:111], v[14:15], v[226:227]
	v_cvt_pk_bf16_f32 v12, v12, v13
	v_cvt_pk_bf16_f32 v13, v14, v15
	global_store_dwordx2 v[46:47], v[12:13], off offset:2048
	v_pk_mul_f32 v[8:9], v[8:9], v[68:69] op_sel_hi:[1,0]
	v_pk_mul_f32 v[10:11], v[10:11], v[68:69] op_sel_hi:[1,0]
	v_pk_mul_f32 v[8:9], v[132:133], v[8:9]
	v_pk_mul_f32 v[10:11], v[134:135], v[10:11]
	v_pk_add_f32 v[164:165], v[196:197], 1.0 op_sel_hi:[1,0]
	v_pk_add_f32 v[110:111], v[198:199], 1.0 op_sel_hi:[1,0]
	v_pk_fma_f32 v[8:9], v[164:165], v[8:9], v[228:229]
	v_pk_fma_f32 v[10:11], v[110:111], v[10:11], v[230:231]
	v_cvt_pk_bf16_f32 v8, v8, v9
	v_cvt_pk_bf16_f32 v9, v10, v11
	global_store_dwordx2 v[46:47], v[8:9], off offset:2560
	v_pk_mul_f32 v[4:5], v[4:5], v[68:69] op_sel_hi:[1,0]
	v_pk_mul_f32 v[6:7], v[6:7], v[68:69] op_sel_hi:[1,0]
	v_pk_mul_f32 v[4:5], v[136:137], v[4:5]
	v_pk_mul_f32 v[6:7], v[138:139], v[6:7]
	v_pk_add_f32 v[164:165], v[200:201], 1.0 op_sel_hi:[1,0]
	v_pk_add_f32 v[110:111], v[202:203], 1.0 op_sel_hi:[1,0]
	v_pk_fma_f32 v[4:5], v[164:165], v[4:5], v[144:145]
	v_pk_fma_f32 v[6:7], v[110:111], v[6:7], v[146:147]
	v_cvt_pk_bf16_f32 v4, v4, v5
	v_cvt_pk_bf16_f32 v5, v6, v7
	global_store_dwordx2 v[46:47], v[4:5], off offset:3072
	v_pk_mul_f32 v[0:1], v[0:1], v[68:69] op_sel_hi:[1,0]
	v_pk_mul_f32 v[2:3], v[2:3], v[68:69] op_sel_hi:[1,0]
	v_pk_mul_f32 v[0:1], v[140:141], v[0:1]
	v_pk_mul_f32 v[2:3], v[142:143], v[2:3]
	v_pk_add_f32 v[164:165], v[204:205], 1.0 op_sel_hi:[1,0]
	v_pk_add_f32 v[110:111], v[206:207], 1.0 op_sel_hi:[1,0]
	v_pk_fma_f32 v[0:1], v[164:165], v[0:1], v[148:149]
	v_pk_fma_f32 v[2:3], v[110:111], v[2:3], v[150:151]
	v_cvt_pk_bf16_f32 v0, v0, v1
	v_cvt_pk_bf16_f32 v1, v2, v3
	global_store_dwordx2 v[46:47], v[0:1], off offset:3584
	v_lshl_add_u64 v[46:47], v[46:47], 0, s[50:51]
	s_or_b64 s[16:17], s[100:101], s[16:17]
	s_andn2_b64 exec, exec, s[16:17]
	s_cbranch_execz .LBB0_53
; __device__ __forceinline__ void phase_norm(const float* xin, const float* g, const float* mod, int shift_off, int scale_off, bf16_t* hout) {
;     ...
;     for (int row = blockIdx.x * 8 + wid; row < NTOK; row += nw) {
;         const int b = row >> 13;
;         const float* xr = xin + (size_t)row * DM;
;         f32x4 v[8]; float ss = 0.f;
; #pragma unroll
;         for (int i = 0; i < 8; ++i) { v[i] = *(const f32x4*)(xr + i * 256 + lane * 4); ss += v[i][0] * v[i][0] + v[i][1] * v[i][1] + v[i][2] * v[i][2] + v[i][3] * v[i][3]; }
;         ss = wave_sum(ss);
;         const float rstd = rsqrtf(ss * (1.0f / DM) + 1e-6f);
;         const float* mb = mod + (size_t)b * 6 * DM;
; #pragma unroll
;         for (int i = 0; i < 8; ++i) {
;             const int col = i * 256 + lane * 4;
;             const f32x4 g4 = *(const f32x4*)(g + col), sc4 = *(const f32x4*)(mb + scale_off + col), sh4 = *(const f32x4*)(mb + shift_off + col);
	v_ashrrev_i32_e32 v35, 13, v34
	s_nop 0
	v_readfirstlane_b32 s99, v35
	s_cmp_eq_u32 s99, s98
	s_cbranch_scc1 .Lnorm1b_params_ok
	s_mov_b32 s98, s99
	v_mul_i32_i24_e32 v160, 6, v35
	v_ashrrev_i32_e32 v161, 31, v160
	v_lshlrev_b64 v[160:161], 13, v[160:161]
	v_lshl_add_u64 v[160:161], s[14:15], 0, v[160:161]
	v_lshl_add_u64 v[162:163], v[160:161], 0, s[10:11]
	v_lshl_add_u64 v[152:153], v[162:163], 0, v[32:33]
	v_lshl_add_u64 v[154:155], v[160:161], 0, v[32:33]
	v_lshl_add_u64 v[156:157], v[162:163], 0, v[56:57]
	v_lshl_add_u64 v[158:159], v[160:161], 0, v[56:57]
	global_load_dwordx4 v[112:115], v[36:37], off
	global_load_dwordx4 v[116:119], v[36:37], off offset:1024
	global_load_dwordx4 v[120:123], v[36:37], off offset:2048
	global_load_dwordx4 v[124:127], v[36:37], off offset:3072
	global_load_dwordx4 v[128:131], v[38:39], off
	global_load_dwordx4 v[132:135], v[38:39], off offset:1024
	global_load_dwordx4 v[136:139], v[38:39], off offset:2048
	global_load_dwordx4 v[140:143], v[38:39], off offset:3072
	global_load_dwordx4 v[176:179], v[152:153], off
	global_load_dwordx4 v[180:183], v[152:153], off offset:1024
	global_load_dwordx4 v[184:187], v[152:153], off offset:2048
	global_load_dwordx4 v[188:191], v[152:153], off offset:3072
	global_load_dwordx4 v[192:195], v[156:157], off
	global_load_dwordx4 v[196:199], v[156:157], off offset:1024
	global_load_dwordx4 v[200:203], v[156:157], off offset:2048
	global_load_dwordx4 v[204:207], v[156:157], off offset:3072
	global_load_dwordx4 v[208:211], v[154:155], off
	global_load_dwordx4 v[212:215], v[154:155], off offset:1024
	global_load_dwordx4 v[216:219], v[154:155], off offset:2048
	global_load_dwordx4 v[220:223], v[154:155], off offset:3072
	global_load_dwordx4 v[224:227], v[158:159], off
	global_load_dwordx4 v[228:231], v[158:159], off offset:1024
	global_load_dwordx4 v[144:147], v[158:159], off offset:2048
	global_load_dwordx4 v[148:151], v[158:159], off offset:3072
	s_waitcnt vmcnt(0)
.Lnorm1b_params_ok:
	v_add_u32_e32 v34, s48, v34
	v_lshl_add_u64 v[48:49], v[48:49], 0, s[52:53]
	v_cmp_lt_i32_e32 vcc, s21, v34
	s_mov_b64 s[100:101], vcc
	s_cbranch_vccnz .Lnorm1b_nopf
	global_load_dwordx4 v[24:27], v[48:49], off offset:-4096
	global_load_dwordx4 v[28:31], v[48:49], off offset:-3072
	global_load_dwordx4 v[20:23], v[48:49], off offset:-2048
	global_load_dwordx4 v[16:19], v[48:49], off offset:-1024
	global_load_dwordx4 v[12:15], v[48:49], off
	global_load_dwordx4 v[8:11], v[48:49], off offset:1024
	global_load_dwordx4 v[4:7], v[48:49], off offset:2048
	global_load_dwordx4 v[0:3], v[48:49], off offset:3072
	s_branch .Lnorm1b_pfdone

; __device__ __forceinline__ unsigned cvt_pk_bf16(float lo, float hi) { unsigned r; asm volatile("v_cvt_pk_bf16_f32 %0, %1, %2" : "=v"(r) : "v"(lo), "v"(hi)); return r; }
; __device__ __forceinline__ void phase_norm(const float* xin, const float* g, const float* mod, int shift_off, int scale_off, bf16_t* hout) {
;     ...
;         for (int i = 0; i < 8; ++i) { v[i] = *(const f32x4*)(xr + i * 256 + lane * 4); ss += v[i][0] * v[i][0] + v[i][1] * v[i][1] + v[i][2] * v[i][2] + v[i][3] * v[i][3]; }
;         ss = wave_sum(ss);
;         const float rstd = rsqrtf(ss * (1.0f / DM) + 1e-6f);
;         const float* mb = mod + (size_t)b * 6 * DM;
; #pragma unroll
;         for (int i = 0; i < 8; ++i) {
;             const int col = i * 256 + lane * 4;
;             const f32x4 g4 = *(const f32x4*)(g + col), sc4 = *(const f32x4*)(mb + scale_off + col), sh4 = *(const f32x4*)(mb + shift_off + col);
;             f32x4 y = (v[i] * rstd) * g4; y = y * (sc4 + 1.0f) + sh4;
;             u32x2 w; w.x = cvt_pk_bf16(y[0], y[1]); w.y = cvt_pk_bf16(y[2], y[3]);
;             *(u32x2*)(hout + (size_t)row * DM + col) = w;
;         }
.Lnorm1b_pfdone:
	s_waitcnt vmcnt(23)
	v_mul_f32_e32 v35, v78, v78
	v_fmac_f32_e32 v35, v79, v79
	v_fmac_f32_e32 v35, v80, v80
	v_fmac_f32_e32 v35, v81, v81
	s_waitcnt vmcnt(22)
	v_mul_f32_e32 v175, v82, v82
	v_fmac_f32_e32 v175, v83, v83
	v_fmac_f32_e32 v175, v84, v84
	v_fmac_f32_e32 v175, v85, v85
	s_waitcnt vmcnt(21)
	v_fmac_f32_e32 v35, v86, v86
	v_fmac_f32_e32 v35, v87, v87
	v_fmac_f32_e32 v35, v88, v88
	v_fmac_f32_e32 v35, v89, v89
	s_waitcnt vmcnt(20)
	v_fmac_f32_e32 v175, v90, v90
	v_fmac_f32_e32 v175, v91, v91
	v_fmac_f32_e32 v175, v92, v92
	v_fmac_f32_e32 v175, v93, v93
	s_waitcnt vmcnt(19)
	v_fmac_f32_e32 v35, v94, v94
	v_fmac_f32_e32 v35, v95, v95
	v_fmac_f32_e32 v35, v96, v96
	v_fmac_f32_e32 v35, v97, v97
	s_waitcnt vmcnt(18)
	v_fmac_f32_e32 v175, v98, v98
	v_fmac_f32_e32 v175, v99, v99
	v_fmac_f32_e32 v175, v100, v100
	v_fmac_f32_e32 v175, v101, v101
	s_waitcnt vmcnt(17)
	v_fmac_f32_e32 v35, v102, v102
	v_fmac_f32_e32 v35, v103, v103
	v_fmac_f32_e32 v35, v104, v104
	v_fmac_f32_e32 v35, v105, v105
	s_waitcnt vmcnt(16)
	v_fmac_f32_e32 v175, v106, v106
	v_fmac_f32_e32 v175, v107, v107
	v_fmac_f32_e32 v175, v108, v108
	v_fmac_f32_e32 v175, v109, v109
	v_add_f32_e32 v35, v35, v175
	ds_bpermute_b32 v68, v72, v35
	s_waitcnt lgkmcnt(0)
	v_add_f32_e32 v35, v35, v68
	ds_bpermute_b32 v68, v73, v35
	s_waitcnt lgkmcnt(0)
	v_add_f32_e32 v35, v35, v68
	ds_bpermute_b32 v68, v74, v35
	s_waitcnt lgkmcnt(0)
	v_add_f32_e32 v35, v35, v68
	ds_bpermute_b32 v68, v75, v35
	s_waitcnt lgkmcnt(0)
	v_add_f32_e32 v35, v35, v68
	ds_bpermute_b32 v68, v76, v35
	s_waitcnt lgkmcnt(0)
	v_add_f32_e32 v35, v35, v68
	ds_bpermute_b32 v68, v77, v35
	s_waitcnt lgkmcnt(0)
	v_add_f32_e32 v35, v35, v68
	v_fmamk_f32 v35, v35, 0x3a000000, v69
	v_mul_f32_e32 v68, 0x4b800000, v35
	v_cmp_gt_f32_e32 vcc, s20, v35
	s_nop 1
	v_cndmask_b32_e32 v35, v35, v68, vcc
	v_rsq_f32_e32 v35, v35
	s_nop 0
	v_mul_f32_e32 v68, 0x45800000, v35
	v_cndmask_b32_e32 v68, v35, v68, vcc
	v_pk_mul_f32 v[78:79], v[78:79], v[68:69] op_sel_hi:[1,0]
	v_pk_mul_f32 v[80:81], v[80:81], v[68:69] op_sel_hi:[1,0]
	v_pk_mul_f32 v[78:79], v[112:113], v[78:79]
	v_pk_mul_f32 v[80:81], v[114:115], v[80:81]
	v_pk_add_f32 v[164:165], v[176:177], 1.0 op_sel_hi:[1,0]
	v_pk_add_f32 v[110:111], v[178:179], 1.0 op_sel_hi:[1,0]
	v_pk_fma_f32 v[78:79], v[164:165], v[78:79], v[208:209]
	v_pk_fma_f32 v[80:81], v[110:111], v[80:81], v[210:211]
	v_cvt_pk_bf16_f32 v78, v78, v79
	v_cvt_pk_bf16_f32 v79, v80, v81
	global_store_dwordx2 v[46:47], v[78:79], off
	v_pk_mul_f32 v[82:83], v[82:83], v[68:69] op_sel_hi:[1,0]
	v_pk_mul_f32 v[84:85], v[84:85], v[68:69] op_sel_hi:[1,0]
	v_pk_mul_f32 v[82:83], v[116:117], v[82:83]
	v_pk_mul_f32 v[84:85], v[118:119], v[84:85]
	v_pk_add_f32 v[164:165], v[180:181], 1.0 op_sel_hi:[1,0]
	v_pk_add_f32 v[110:111], v[182:183], 1.0 op_sel_hi:[1,0]
	v_pk_fma_f32 v[82:83], v[164:165], v[82:83], v[212:213]
	v_pk_fma_f32 v[84:85], v[110:111], v[84:85], v[214:215]
	v_cvt_pk_bf16_f32 v82, v82, v83
	v_cvt_pk_bf16_f32 v83, v84, v85
	global_store_dwordx2 v[46:47], v[82:83], off offset:512
	v_pk_mul_f32 v[86:87], v[86:87], v[68:69] op_sel_hi:[1,0]
	v_pk_mul_f32 v[88:89], v[88:89], v[68:69] op_sel_hi:[1,0]
	v_pk_mul_f32 v[86:87], v[120:121], v[86:87]
	v_pk_mul_f32 v[88:89], v[122:123], v[88:89]
	v_pk_add_f32 v[164:165], v[184:185], 1.0 op_sel_hi:[1,0]
	v_pk_add_f32 v[110:111], v[186:187], 1.0 op_sel_hi:[1,0]
	v_pk_fma_f32 v[86:87], v[164:165], v[86:87], v[216:217]
	v_pk_fma_f32 v[88:89], v[110:111], v[88:89], v[218:219]
	v_cvt_pk_bf16_f32 v86, v86, v87
	v_cvt_pk_bf16_f32 v87, v88, v89
	global_store_dwordx2 v[46:47], v[86:87], off offset:1024
	v_pk_mul_f32 v[90:91], v[90:91], v[68:69] op_sel_hi:[1,0]
	v_pk_mul_f32 v[92:93], v[92:93], v[68:69] op_sel_hi:[1,0]
	v_pk_mul_f32 v[90:91], v[124:125], v[90:91]
	v_pk_mul_f32 v[92:93], v[126:127], v[92:93]
	v_pk_add_f32 v[164:165], v[188:189], 1.0 op_sel_hi:[1,0]
	v_pk_add_f32 v[110:111], v[190:191], 1.0 op_sel_hi:[1,0]
	v_pk_fma_f32 v[90:91], v[164:165], v[90:91], v[220:221]
	v_pk_fma_f32 v[92:93], v[110:111], v[92:93], v[222:223]
	v_cvt_pk_bf16_f32 v90, v90, v91
	v_cvt_pk_bf16_f32 v91, v92, v93
	global_store_dwordx2 v[46:47], v[90:91], off offset:1536
	v_pk_mul_f32 v[94:95], v[94:95], v[68:69] op_sel_hi:[1,0]
	v_pk_mul_f32 v[96:97], v[96:97], v[68:69] op_sel_hi:[1,0]
	v_pk_mul_f32 v[94:95], v[128:129], v[94:95]
	v_pk_mul_f32 v[96:97], v[130:131], v[96:97]
	v_pk_add_f32 v[164:165], v[192:193], 1.0 op_sel_hi:[1,0]
	v_pk_add_f32 v[110:111], v[194:195], 1.0 op_sel_hi:[1,0]
	v_pk_fma_f32 v[94:95], v[164:165], v[94:95], v[224:225]
	v_pk_fma_f32 v[96:97], v[110:111], v[96:97], v[226:227]
	v_cvt_pk_bf16_f32 v94, v94, v95
	v_cvt_pk_bf16_f32 v95, v96, v97
	global_store_dwordx2 v[46:47], v[94:95], off offset:2048
	v_pk_mul_f32 v[98:99], v[98:99], v[68:69] op_sel_hi:[1,0]
	v_pk_mul_f32 v[100:101], v[100:101], v[68:69] op_sel_hi:[1,0]
	v_pk_mul_f32 v[98:99], v[132:133], v[98:99]
	v_pk_mul_f32 v[100:101], v[134:135], v[100:101]
	v_pk_add_f32 v[164:165], v[196:197], 1.0 op_sel_hi:[1,0]
	v_pk_add_f32 v[110:111], v[198:199], 1.0 op_sel_hi:[1,0]
	v_pk_fma_f32 v[98:99], v[164:165], v[98:99], v[228:229]
	v_pk_fma_f32 v[100:101], v[110:111], v[100:101], v[230:231]
	v_cvt_pk_bf16_f32 v98, v98, v99
	v_cvt_pk_bf16_f32 v99, v100, v101
	global_store_dwordx2 v[46:47], v[98:99], off offset:2560
	v_pk_mul_f32 v[102:103], v[102:103], v[68:69] op_sel_hi:[1,0]
	v_pk_mul_f32 v[104:105], v[104:105], v[68:69] op_sel_hi:[1,0]
	v_pk_mul_f32 v[102:103], v[136:137], v[102:103]
	v_pk_mul_f32 v[104:105], v[138:139], v[104:105]
	v_pk_add_f32 v[164:165], v[200:201], 1.0 op_sel_hi:[1,0]
	v_pk_add_f32 v[110:111], v[202:203], 1.0 op_sel_hi:[1,0]
	v_pk_fma_f32 v[102:103], v[164:165], v[102:103], v[144:145]
	v_pk_fma_f32 v[104:105], v[110:111], v[104:105], v[146:147]
	v_cvt_pk_bf16_f32 v102, v102, v103
	v_cvt_pk_bf16_f32 v103, v104, v105
	global_store_dwordx2 v[46:47], v[102:103], off offset:3072
	v_pk_mul_f32 v[106:107], v[106:107], v[68:69] op_sel_hi:[1,0]
	v_pk_mul_f32 v[108:109], v[108:109], v[68:69] op_sel_hi:[1,0]
	v_pk_mul_f32 v[106:107], v[140:141], v[106:107]
	v_pk_mul_f32 v[108:109], v[142:143], v[108:109]
	v_pk_add_f32 v[164:165], v[204:205], 1.0 op_sel_hi:[1,0]
	v_pk_add_f32 v[110:111], v[206:207], 1.0 op_sel_hi:[1,0]
	v_pk_fma_f32 v[106:107], v[164:165], v[106:107], v[148:149]
	v_pk_fma_f32 v[108:109], v[110:111], v[108:109], v[150:151]
	v_cvt_pk_bf16_f32 v106, v106, v107
	v_cvt_pk_bf16_f32 v107, v108, v109
	global_store_dwordx2 v[46:47], v[106:107], off offset:3584
	v_lshl_add_u64 v[46:47], v[46:47], 0, s[50:51]
	s_or_b64 s[16:17], s[100:101], s[16:17]
	s_andn2_b64 exec, exec, s[16:17]
	s_cbranch_execz .LBB0_53
	s_branch .LBB0_56

; __device__ __forceinline__ void phase_norm(const float* xin, const float* g, const float* mod, int shift_off, int scale_off, bf16_t* hout) {
;     ...
;     for (int row = blockIdx.x * 8 + wid; row < NTOK; row += nw) {
;         const int b = row >> 13;
;         const float* xr = xin + (size_t)row * DM;
;         f32x4 v[8]; float ss = 0.f;
; #pragma unroll
;         for (int i = 0; i < 8; ++i) { v[i] = *(const f32x4*)(xr + i * 256 + lane * 4); ss += v[i][0] * v[i][0] + v[i][1] * v[i][1] + v[i][2] * v[i][2] + v[i][3] * v[i][3]; }
;         ss = wave_sum(ss);
;         const float rstd = rsqrtf(ss * (1.0f / DM) + 1e-6f);
;         const float* mb = mod + (size_t)b * 6 * DM;
; #pragma unroll
;         for (int i = 0; i < 8; ++i) {
;             const int col = i * 256 + lane * 4;
;             const f32x4 g4 = *(const f32x4*)(g + col), sc4 = *(const f32x4*)(mb + scale_off + col), sh4 = *(const f32x4*)(mb + shift_off + col);
.LBB0_1896:
	s_mov_b64 s[26:27], s[0:1]
	v_mov_b32_e32 v0, v166
	s_nop 0
	v_ashrrev_i32_e32 v1, 6, v0
	v_add_u32_e32 v30, s70, v1
	v_cmp_gt_i32_e32 vcc, s30, v30
	s_and_saveexec_b64 s[24:25], vcc
	s_cbranch_execz .LBB0_1895
	v_lshlrev_b32_e32 v1, 2, v0
	v_cmp_lt_i32_e32 vcc, v169, v168
	v_and_b32_e32 v2, 0xfc, v1
	s_load_dwordx4 s[8:11], s[26:27], 0x78
	s_load_dwordx2 s[4:5], s[26:27], 0x28
	v_cndmask_b32_e32 v1, v167, v169, vcc
	v_cmp_lt_i32_e32 vcc, v170, v168
	v_lshlrev_b32_e32 v66, 2, v1
	v_ashrrev_i32_e32 v31, 31, v30
	v_cndmask_b32_e32 v1, v167, v170, vcc
	v_cmp_lt_i32_e32 vcc, v171, v168
	v_lshlrev_b32_e32 v67, 2, v1
	v_lshlrev_b64 v[18:19], 12, v[30:31]
	v_cndmask_b32_e32 v1, v167, v171, vcc
	v_cmp_lt_i32_e32 vcc, v172, v168
	s_waitcnt vmcnt(4)
	v_lshlrev_b32_e32 v68, 2, v1
	v_and_b32_e32 v3, 63, v0
	v_cndmask_b32_e32 v1, v167, v172, vcc
	v_cmp_lt_i32_e32 vcc, v173, v168
	v_lshlrev_b32_e32 v69, 2, v1
	v_lshlrev_b32_e32 v28, 2, v2
	v_cndmask_b32_e32 v1, v167, v173, vcc
	v_cmp_lt_i32_e32 vcc, v174, v168
	v_lshlrev_b32_e32 v70, 2, v1
	v_or_b32_e32 v10, 0x400, v2
	v_cndmask_b32_e32 v1, v167, v174, vcc
	v_lshl_or_b32 v18, v3, 3, v18
	v_lshlrev_b32_e32 v71, 2, v1
	s_waitcnt lgkmcnt(0)
	v_lshl_add_u64 v[32:33], s[4:5], 0, v[28:29]
	v_lshlrev_b32_e32 v28, 2, v10
	v_or_b32_e32 v12, 0x500, v2
	v_lshl_add_u64 v[0:1], s[10:11], 0, v[18:19]
	v_lshl_add_u64 v[34:35], s[4:5], 0, v[28:29]
	v_lshlrev_b32_e32 v28, 2, v12
	v_or_b32_e32 v14, 0x600, v2
	v_lshl_add_u64 v[42:43], v[0:1], 0, s[12:13]
	v_lshlrev_b64 v[0:1], 13, v[30:31]
	v_lshl_add_u64 v[36:37], s[4:5], 0, v[28:29]
	v_lshlrev_b32_e32 v28, 2, v14
	v_or_b32_e32 v16, 0x700, v2
	v_lshl_or_b32 v0, v3, 4, v0
	s_add_u32 s26, s10, 0x6300000
	v_or_b32_e32 v4, 0x100, v2
	v_or_b32_e32 v6, 0x200, v2
	v_or_b32_e32 v8, 0x300, v2
	v_lshl_add_u64 v[38:39], s[4:5], 0, v[28:29]
	v_lshlrev_b32_e32 v28, 2, v16
	v_lshl_add_u64 v[0:1], s[8:9], 0, v[0:1]
	s_addc_u32 s27, s11, 0
	v_lshl_add_u64 v[40:41], s[4:5], 0, v[28:29]
	v_lshl_add_u64 v[44:45], v[0:1], 0, s[14:15]
	s_mov_b64 s[8:9], 0
	v_lshlrev_b32_e32 v28, 2, v2
	v_lshlrev_b32_e32 v46, 2, v4
	v_lshlrev_b32_e32 v48, 2, v6
	v_lshlrev_b32_e32 v50, 2, v8
	v_lshlrev_b32_e32 v52, 2, v10
	v_lshlrev_b32_e32 v54, 2, v12
	v_lshlrev_b32_e32 v56, 2, v14
	v_lshlrev_b32_e32 v58, 2, v16
	v_mov_b32_e32 v47, v29
	v_mov_b32_e32 v49, v29
	v_mov_b32_e32 v51, v29
	v_mov_b32_e32 v53, v29
	v_mov_b32_e32 v55, v29
	v_mov_b32_e32 v57, v29
	v_mov_b32_e32 v59, v29
	s_mov_b32 s98, -1
	global_load_dwordx4 v[72:75], v[44:45], off offset:-4096
	global_load_dwordx4 v[24:27], v[44:45], off offset:-3072
	global_load_dwordx4 v[20:23], v[44:45], off offset:-2048
	global_load_dwordx4 v[16:19], v[44:45], off offset:-1024
	global_load_dwordx4 v[12:15], v[44:45], off
	global_load_dwordx4 v[8:11], v[44:45], off offset:1024
	global_load_dwordx4 v[4:7], v[44:45], off offset:2048
	global_load_dwordx4 v[0:3], v[44:45], off offset:3072
	s_waitcnt vmcnt(0)
.LBB0_1898:
	v_ashrrev_i32_e32 v31, 13, v30
	s_nop 0
	v_readfirstlane_b32 s99, v31
	s_cmp_eq_u32 s99, s98
	s_cbranch_scc1 .Lnorm2a_params_ok
	s_mov_b32 s98, s99
	v_mul_i32_i24_e32 v160, 6, v31
	v_ashrrev_i32_e32 v161, 31, v160
	v_lshlrev_b64 v[160:161], 13, v[160:161]
	v_lshl_add_u64 v[160:161], s[26:27], 0, v[160:161]
	v_lshl_add_u64 v[162:163], v[160:161], 0, s[20:21]
	v_lshl_add_u64 v[160:161], v[160:161], 0, s[22:23]
	v_lshl_add_u64 v[152:153], v[162:163], 0, v[28:29]
	v_lshl_add_u64 v[154:155], v[160:161], 0, v[28:29]
	v_lshl_add_u64 v[156:157], v[162:163], 0, v[52:53]
	v_lshl_add_u64 v[158:159], v[160:161], 0, v[52:53]
	global_load_dwordx4 v[112:115], v[32:33], off
	global_load_dwordx4 v[116:119], v[32:33], off offset:1024
	global_load_dwordx4 v[120:123], v[32:33], off offset:2048
	global_load_dwordx4 v[124:127], v[32:33], off offset:3072
	global_load_dwordx4 v[128:131], v[34:35], off
	global_load_dwordx4 v[132:135], v[34:35], off offset:1024
	global_load_dwordx4 v[136:139], v[34:35], off offset:2048
	global_load_dwordx4 v[140:143], v[34:35], off offset:3072
	global_load_dwordx4 v[176:179], v[152:153], off
	global_load_dwordx4 v[180:183], v[152:153], off offset:1024
	global_load_dwordx4 v[184:187], v[152:153], off offset:2048
	global_load_dwordx4 v[188:191], v[152:153], off offset:3072
	global_load_dwordx4 v[192:195], v[156:157], off
	global_load_dwordx4 v[196:199], v[156:157], off offset:1024
	global_load_dwordx4 v[200:203], v[156:157], off offset:2048
	global_load_dwordx4 v[204:207], v[156:157], off offset:3072
	global_load_dwordx4 v[208:211], v[154:155], off
	global_load_dwordx4 v[212:215], v[154:155], off offset:1024
	global_load_dwordx4 v[216:219], v[154:155], off offset:2048
	global_load_dwordx4 v[220:223], v[154:155], off offset:3072
	global_load_dwordx4 v[224:227], v[158:159], off
	global_load_dwordx4 v[228:231], v[158:159], off offset:1024
	global_load_dwordx4 v[144:147], v[158:159], off offset:2048
	global_load_dwordx4 v[148:151], v[158:159], off offset:3072
	s_waitcnt vmcnt(0)
.Lnorm2a_params_ok:
	v_add_u32_e32 v30, s48, v30
	v_lshl_add_u64 v[44:45], v[44:45], 0, s[52:53]
	v_cmp_lt_i32_e32 vcc, s34, v30
	s_mov_b64 s[100:101], vcc
	s_cbranch_vccnz .Lnorm2a_nopf
	global_load_dwordx4 v[76:79], v[44:45], off offset:-4096
	global_load_dwordx4 v[80:83], v[44:45], off offset:-3072
	global_load_dwordx4 v[84:87], v[44:45], off offset:-2048
	global_load_dwordx4 v[88:91], v[44:45], off offset:-1024
	global_load_dwordx4 v[92:95], v[44:45], off
	global_load_dwordx4 v[96:99], v[44:45], off offset:1024
	global_load_dwordx4 v[100:103], v[44:45], off offset:2048
	global_load_dwordx4 v[104:107], v[44:45], off offset:3072
	s_branch .Lnorm2a_pfdone

; __device__ __forceinline__ unsigned cvt_pk_bf16(float lo, float hi) { unsigned r; asm volatile("v_cvt_pk_bf16_f32 %0, %1, %2" : "=v"(r) : "v"(lo), "v"(hi)); return r; }
; __device__ __forceinline__ void phase_norm(const float* xin, const float* g, const float* mod, int shift_off, int scale_off, bf16_t* hout) {
;     ...
;         for (int i = 0; i < 8; ++i) { v[i] = *(const f32x4*)(xr + i * 256 + lane * 4); ss += v[i][0] * v[i][0] + v[i][1] * v[i][1] + v[i][2] * v[i][2] + v[i][3] * v[i][3]; }
;         ss = wave_sum(ss);
;         const float rstd = rsqrtf(ss * (1.0f / DM) + 1e-6f);
;         const float* mb = mod + (size_t)b * 6 * DM;
; #pragma unroll
;         for (int i = 0; i < 8; ++i) {
;             const int col = i * 256 + lane * 4;
;             const f32x4 g4 = *(const f32x4*)(g + col), sc4 = *(const f32x4*)(mb + scale_off + col), sh4 = *(const f32x4*)(mb + shift_off + col);
;             f32x4 y = (v[i] * rstd) * g4; y = y * (sc4 + 1.0f) + sh4;
;             u32x2 w; w.x = cvt_pk_bf16(y[0], y[1]); w.y = cvt_pk_bf16(y[2], y[3]);
;             *(u32x2*)(hout + (size_t)row * DM + col) = w;
;         }
.Lnorm2a_pfdone:
	s_waitcnt vmcnt(23)
	v_mul_f32_e32 v31, v72, v72
	v_fmac_f32_e32 v31, v73, v73
	v_fmac_f32_e32 v31, v74, v74
	v_fmac_f32_e32 v31, v75, v75
	s_waitcnt vmcnt(22)
	v_mul_f32_e32 v175, v24, v24
	v_fmac_f32_e32 v175, v25, v25
	v_fmac_f32_e32 v175, v26, v26
	v_fmac_f32_e32 v175, v27, v27
	s_waitcnt vmcnt(21)
	v_fmac_f32_e32 v31, v20, v20
	v_fmac_f32_e32 v31, v21, v21
	v_fmac_f32_e32 v31, v22, v22
	v_fmac_f32_e32 v31, v23, v23
	s_waitcnt vmcnt(20)
	v_fmac_f32_e32 v175, v16, v16
	v_fmac_f32_e32 v175, v17, v17
	v_fmac_f32_e32 v175, v18, v18
	v_fmac_f32_e32 v175, v19, v19
	s_waitcnt vmcnt(19)
	v_fmac_f32_e32 v31, v12, v12
	v_fmac_f32_e32 v31, v13, v13
	v_fmac_f32_e32 v31, v14, v14
	v_fmac_f32_e32 v31, v15, v15
	s_waitcnt vmcnt(18)
	v_fmac_f32_e32 v175, v8, v8
	v_fmac_f32_e32 v175, v9, v9
	v_fmac_f32_e32 v175, v10, v10
	v_fmac_f32_e32 v175, v11, v11
	s_waitcnt vmcnt(17)
	v_fmac_f32_e32 v31, v4, v4
	v_fmac_f32_e32 v31, v5, v5
	v_fmac_f32_e32 v31, v6, v6
	v_fmac_f32_e32 v31, v7, v7
	s_waitcnt vmcnt(16)
	v_fmac_f32_e32 v175, v0, v0
	v_fmac_f32_e32 v175, v1, v1
	v_fmac_f32_e32 v175, v2, v2
	v_fmac_f32_e32 v175, v3, v3
	v_add_f32_e32 v31, v31, v175
	ds_bpermute_b32 v64, v66, v31
	s_waitcnt lgkmcnt(0)
	v_add_f32_e32 v31, v31, v64
	ds_bpermute_b32 v64, v67, v31
	s_waitcnt lgkmcnt(0)
	v_add_f32_e32 v31, v31, v64
	ds_bpermute_b32 v64, v68, v31
	s_waitcnt lgkmcnt(0)
	v_add_f32_e32 v31, v31, v64
	ds_bpermute_b32 v64, v69, v31
	s_waitcnt lgkmcnt(0)
	v_add_f32_e32 v31, v31, v64
	ds_bpermute_b32 v64, v70, v31
	s_waitcnt lgkmcnt(0)
	v_add_f32_e32 v31, v31, v64
	ds_bpermute_b32 v64, v71, v31
	s_waitcnt lgkmcnt(0)
	v_add_f32_e32 v31, v31, v64
	v_fmamk_f32 v31, v31, 0x3a000000, v65
	v_mul_f32_e32 v64, 0x4b800000, v31
	v_cmp_gt_f32_e32 vcc, s31, v31
	s_nop 1
	v_cndmask_b32_e32 v31, v31, v64, vcc
	v_rsq_f32_e32 v31, v31
	s_nop 0
	v_mul_f32_e32 v64, 0x45800000, v31
	v_cndmask_b32_e32 v64, v31, v64, vcc
	v_pk_mul_f32 v[72:73], v[72:73], v[64:65] op_sel_hi:[1,0]
	v_pk_mul_f32 v[74:75], v[74:75], v[64:65] op_sel_hi:[1,0]
	v_pk_mul_f32 v[72:73], v[112:113], v[72:73]
	v_pk_mul_f32 v[74:75], v[114:115], v[74:75]
	v_pk_add_f32 v[164:165], v[176:177], 1.0 op_sel_hi:[1,0]
	v_pk_add_f32 v[110:111], v[178:179], 1.0 op_sel_hi:[1,0]
	v_pk_fma_f32 v[72:73], v[164:165], v[72:73], v[208:209]
	v_pk_fma_f32 v[74:75], v[110:111], v[74:75], v[210:211]
	v_cvt_pk_bf16_f32 v72, v72, v73
	v_cvt_pk_bf16_f32 v73, v74, v75
	global_store_dwordx2 v[42:43], v[72:73], off
	v_pk_mul_f32 v[24:25], v[24:25], v[64:65] op_sel_hi:[1,0]
	v_pk_mul_f32 v[26:27], v[26:27], v[64:65] op_sel_hi:[1,0]
	v_pk_mul_f32 v[24:25], v[116:117], v[24:25]
	v_pk_mul_f32 v[26:27], v[118:119], v[26:27]
	v_pk_add_f32 v[164:165], v[180:181], 1.0 op_sel_hi:[1,0]
	v_pk_add_f32 v[110:111], v[182:183], 1.0 op_sel_hi:[1,0]
	v_pk_fma_f32 v[24:25], v[164:165], v[24:25], v[212:213]
	v_pk_fma_f32 v[26:27], v[110:111], v[26:27], v[214:215]
	v_cvt_pk_bf16_f32 v24, v24, v25
	v_cvt_pk_bf16_f32 v25, v26, v27
	global_store_dwordx2 v[42:43], v[24:25], off offset:512
	v_pk_mul_f32 v[20:21], v[20:21], v[64:65] op_sel_hi:[1,0]
	v_pk_mul_f32 v[22:23], v[22:23], v[64:65] op_sel_hi:[1,0]
	v_pk_mul_f32 v[20:21], v[120:121], v[20:21]
	v_pk_mul_f32 v[22:23], v[122:123], v[22:23]
	v_pk_add_f32 v[164:165], v[184:185], 1.0 op_sel_hi:[1,0]
	v_pk_add_f32 v[110:111], v[186:187], 1.0 op_sel_hi:[1,0]
	v_pk_fma_f32 v[20:21], v[164:165], v[20:21], v[216:217]
	v_pk_fma_f32 v[22:23], v[110:111], v[22:23], v[218:219]
	v_cvt_pk_bf16_f32 v20, v20, v21
	v_cvt_pk_bf16_f32 v21, v22, v23
	global_store_dwordx2 v[42:43], v[20:21], off offset:1024
	v_pk_mul_f32 v[16:17], v[16:17], v[64:65] op_sel_hi:[1,0]
	v_pk_mul_f32 v[18:19], v[18:19], v[64:65] op_sel_hi:[1,0]
	v_pk_mul_f32 v[16:17], v[124:125], v[16:17]
	v_pk_mul_f32 v[18:19], v[126:127], v[18:19]
	v_pk_add_f32 v[164:165], v[188:189], 1.0 op_sel_hi:[1,0]
	v_pk_add_f32 v[110:111], v[190:191], 1.0 op_sel_hi:[1,0]
	v_pk_fma_f32 v[16:17], v[164:165], v[16:17], v[220:221]
	v_pk_fma_f32 v[18:19], v[110:111], v[18:19], v[222:223]
	v_cvt_pk_bf16_f32 v16, v16, v17
	v_cvt_pk_bf16_f32 v17, v18, v19
	global_store_dwordx2 v[42:43], v[16:17], off offset:1536
	v_pk_mul_f32 v[12:13], v[12:13], v[64:65] op_sel_hi:[1,0]
	v_pk_mul_f32 v[14:15], v[14:15], v[64:65] op_sel_hi:[1,0]
	v_pk_mul_f32 v[12:13], v[128:129], v[12:13]
	v_pk_mul_f32 v[14:15], v[130:131], v[14:15]
	v_pk_add_f32 v[164:165], v[192:193], 1.0 op_sel_hi:[1,0]
	v_pk_add_f32 v[110:111], v[194:195], 1.0 op_sel_hi:[1,0]
	v_pk_fma_f32 v[12:13], v[164:165], v[12:13], v[224:225]
	v_pk_fma_f32 v[14:15], v[110:111], v[14:15], v[226:227]
	v_cvt_pk_bf16_f32 v12, v12, v13
	v_cvt_pk_bf16_f32 v13, v14, v15
	global_store_dwordx2 v[42:43], v[12:13], off offset:2048
	v_pk_mul_f32 v[8:9], v[8:9], v[64:65] op_sel_hi:[1,0]
	v_pk_mul_f32 v[10:11], v[10:11], v[64:65] op_sel_hi:[1,0]
	v_pk_mul_f32 v[8:9], v[132:133], v[8:9]
	v_pk_mul_f32 v[10:11], v[134:135], v[10:11]
	v_pk_add_f32 v[164:165], v[196:197], 1.0 op_sel_hi:[1,0]
	v_pk_add_f32 v[110:111], v[198:199], 1.0 op_sel_hi:[1,0]
	v_pk_fma_f32 v[8:9], v[164:165], v[8:9], v[228:229]
	v_pk_fma_f32 v[10:11], v[110:111], v[10:11], v[230:231]
	v_cvt_pk_bf16_f32 v8, v8, v9
	v_cvt_pk_bf16_f32 v9, v10, v11
	global_store_dwordx2 v[42:43], v[8:9], off offset:2560
	v_pk_mul_f32 v[4:5], v[4:5], v[64:65] op_sel_hi:[1,0]
	v_pk_mul_f32 v[6:7], v[6:7], v[64:65] op_sel_hi:[1,0]
	v_pk_mul_f32 v[4:5], v[136:137], v[4:5]
	v_pk_mul_f32 v[6:7], v[138:139], v[6:7]
	v_pk_add_f32 v[164:165], v[200:201], 1.0 op_sel_hi:[1,0]
	v_pk_add_f32 v[110:111], v[202:203], 1.0 op_sel_hi:[1,0]
	v_pk_fma_f32 v[4:5], v[164:165], v[4:5], v[144:145]
	v_pk_fma_f32 v[6:7], v[110:111], v[6:7], v[146:147]
	v_cvt_pk_bf16_f32 v4, v4, v5
	v_cvt_pk_bf16_f32 v5, v6, v7
	global_store_dwordx2 v[42:43], v[4:5], off offset:3072
	v_pk_mul_f32 v[0:1], v[0:1], v[64:65] op_sel_hi:[1,0]
	v_pk_mul_f32 v[2:3], v[2:3], v[64:65] op_sel_hi:[1,0]
	v_pk_mul_f32 v[0:1], v[140:141], v[0:1]
	v_pk_mul_f32 v[2:3], v[142:143], v[2:3]
	v_pk_add_f32 v[164:165], v[204:205], 1.0 op_sel_hi:[1,0]
	v_pk_add_f32 v[110:111], v[206:207], 1.0 op_sel_hi:[1,0]
	v_pk_fma_f32 v[0:1], v[164:165], v[0:1], v[148:149]
	v_pk_fma_f32 v[2:3], v[110:111], v[2:3], v[150:151]
	v_cvt_pk_bf16_f32 v0, v0, v1
	v_cvt_pk_bf16_f32 v1, v2, v3
	global_store_dwordx2 v[42:43], v[0:1], off offset:3584
	v_lshl_add_u64 v[42:43], v[42:43], 0, s[50:51]
	s_or_b64 s[8:9], s[100:101], s[8:9]
	s_andn2_b64 exec, exec, s[8:9]
	s_cbranch_execz .LBB0_1895
; __device__ __forceinline__ void phase_norm(const float* xin, const float* g, const float* mod, int shift_off, int scale_off, bf16_t* hout) {
;     ...
;     for (int row = blockIdx.x * 8 + wid; row < NTOK; row += nw) {
;         const int b = row >> 13;
;         const float* xr = xin + (size_t)row * DM;
;         f32x4 v[8]; float ss = 0.f;
; #pragma unroll
;         for (int i = 0; i < 8; ++i) { v[i] = *(const f32x4*)(xr + i * 256 + lane * 4); ss += v[i][0] * v[i][0] + v[i][1] * v[i][1] + v[i][2] * v[i][2] + v[i][3] * v[i][3]; }
;         ss = wave_sum(ss);
;         const float rstd = rsqrtf(ss * (1.0f / DM) + 1e-6f);
;         const float* mb = mod + (size_t)b * 6 * DM;
; #pragma unroll
;         for (int i = 0; i < 8; ++i) {
;             const int col = i * 256 + lane * 4;
;             const f32x4 g4 = *(const f32x4*)(g + col), sc4 = *(const f32x4*)(mb + scale_off + col), sh4 = *(const f32x4*)(mb + shift_off + col);
	v_ashrrev_i32_e32 v31, 13, v30
	s_nop 0
	v_readfirstlane_b32 s99, v31
	s_cmp_eq_u32 s99, s98
	s_cbranch_scc1 .Lnorm2b_params_ok
	s_mov_b32 s98, s99
	v_mul_i32_i24_e32 v160, 6, v31
	v_ashrrev_i32_e32 v161, 31, v160
	v_lshlrev_b64 v[160:161], 13, v[160:161]
	v_lshl_add_u64 v[160:161], s[26:27], 0, v[160:161]
	v_lshl_add_u64 v[162:163], v[160:161], 0, s[20:21]
	v_lshl_add_u64 v[160:161], v[160:161], 0, s[22:23]
	v_lshl_add_u64 v[152:153], v[162:163], 0, v[28:29]
	v_lshl_add_u64 v[154:155], v[160:161], 0, v[28:29]
	v_lshl_add_u64 v[156:157], v[162:163], 0, v[52:53]
	v_lshl_add_u64 v[158:159], v[160:161], 0, v[52:53]
	global_load_dwordx4 v[112:115], v[32:33], off
	global_load_dwordx4 v[116:119], v[32:33], off offset:1024
	global_load_dwordx4 v[120:123], v[32:33], off offset:2048
	global_load_dwordx4 v[124:127], v[32:33], off offset:3072
	global_load_dwordx4 v[128:131], v[34:35], off
	global_load_dwordx4 v[132:135], v[34:35], off offset:1024
	global_load_dwordx4 v[136:139], v[34:35], off offset:2048
	global_load_dwordx4 v[140:143], v[34:35], off offset:3072
	global_load_dwordx4 v[176:179], v[152:153], off
	global_load_dwordx4 v[180:183], v[152:153], off offset:1024
	global_load_dwordx4 v[184:187], v[152:153], off offset:2048
	global_load_dwordx4 v[188:191], v[152:153], off offset:3072
	global_load_dwordx4 v[192:195], v[156:157], off
	global_load_dwordx4 v[196:199], v[156:157], off offset:1024
	global_load_dwordx4 v[200:203], v[156:157], off offset:2048
	global_load_dwordx4 v[204:207], v[156:157], off offset:3072
	global_load_dwordx4 v[208:211], v[154:155], off
	global_load_dwordx4 v[212:215], v[154:155], off offset:1024
	global_load_dwordx4 v[216:219], v[154:155], off offset:2048
	global_load_dwordx4 v[220:223], v[154:155], off offset:3072
	global_load_dwordx4 v[224:227], v[158:159], off
	global_load_dwordx4 v[228:231], v[158:159], off offset:1024
	global_load_dwordx4 v[144:147], v[158:159], off offset:2048
	global_load_dwordx4 v[148:151], v[158:159], off offset:3072
	s_waitcnt vmcnt(0)
.Lnorm2b_params_ok:
	v_add_u32_e32 v30, s48, v30
	v_lshl_add_u64 v[44:45], v[44:45], 0, s[52:53]
	v_cmp_lt_i32_e32 vcc, s34, v30
	s_mov_b64 s[100:101], vcc
	s_cbranch_vccnz .Lnorm2b_nopf
	global_load_dwordx4 v[72:75], v[44:45], off offset:-4096
	global_load_dwordx4 v[24:27], v[44:45], off offset:-3072
	global_load_dwordx4 v[20:23], v[44:45], off offset:-2048
	global_load_dwordx4 v[16:19], v[44:45], off offset:-1024
	global_load_dwordx4 v[12:15], v[44:45], off
	global_load_dwordx4 v[8:11], v[44:45], off offset:1024
	global_load_dwordx4 v[4:7], v[44:45], off offset:2048
	global_load_dwordx4 v[0:3], v[44:45], off offset:3072
	s_branch .Lnorm2b_pfdone

; __device__ __forceinline__ unsigned cvt_pk_bf16(float lo, float hi) { unsigned r; asm volatile("v_cvt_pk_bf16_f32 %0, %1, %2" : "=v"(r) : "v"(lo), "v"(hi)); return r; }
; __device__ __forceinline__ void phase_norm(const float* xin, const float* g, const float* mod, int shift_off, int scale_off, bf16_t* hout) {
;     ...
;     for (int row = blockIdx.x * 8 + wid; row < NTOK; row += nw) {
;         const int b = row >> 13;
;         const float* xr = xin + (size_t)row * DM;
;         f32x4 v[8]; float ss = 0.f;
; #pragma unroll
;         for (int i = 0; i < 8; ++i) { v[i] = *(const f32x4*)(xr + i * 256 + lane * 4); ss += v[i][0] * v[i][0] + v[i][1] * v[i][1] + v[i][2] * v[i][2] + v[i][3] * v[i][3]; }
;         ss = wave_sum(ss);
;         const float rstd = rsqrtf(ss * (1.0f / DM) + 1e-6f);
;         const float* mb = mod + (size_t)b * 6 * DM;
; #pragma unroll
;         for (int i = 0; i < 8; ++i) {
;             const int col = i * 256 + lane * 4;
;             const f32x4 g4 = *(const f32x4*)(g + col), sc4 = *(const f32x4*)(mb + scale_off + col), sh4 = *(const f32x4*)(mb + shift_off + col);
;             f32x4 y = (v[i] * rstd) * g4; y = y * (sc4 + 1.0f) + sh4;
;             u32x2 w; w.x = cvt_pk_bf16(y[0], y[1]); w.y = cvt_pk_bf16(y[2], y[3]);
;             *(u32x2*)(hout + (size_t)row * DM + col) = w;
;         }
;     }
.Lnorm2b_pfdone:
	s_waitcnt vmcnt(23)
	v_mul_f32_e32 v31, v76, v76
	v_fmac_f32_e32 v31, v77, v77
	v_fmac_f32_e32 v31, v78, v78
	v_fmac_f32_e32 v31, v79, v79
	s_waitcnt vmcnt(22)
	v_mul_f32_e32 v175, v80, v80
	v_fmac_f32_e32 v175, v81, v81
	v_fmac_f32_e32 v175, v82, v82
	v_fmac_f32_e32 v175, v83, v83
	s_waitcnt vmcnt(21)
	v_fmac_f32_e32 v31, v84, v84
	v_fmac_f32_e32 v31, v85, v85
	v_fmac_f32_e32 v31, v86, v86
	v_fmac_f32_e32 v31, v87, v87
	s_waitcnt vmcnt(20)
	v_fmac_f32_e32 v175, v88, v88
	v_fmac_f32_e32 v175, v89, v89
	v_fmac_f32_e32 v175, v90, v90
	v_fmac_f32_e32 v175, v91, v91
	s_waitcnt vmcnt(19)
	v_fmac_f32_e32 v31, v92, v92
	v_fmac_f32_e32 v31, v93, v93
	v_fmac_f32_e32 v31, v94, v94
	v_fmac_f32_e32 v31, v95, v95
	s_waitcnt vmcnt(18)
	v_fmac_f32_e32 v175, v96, v96
	v_fmac_f32_e32 v175, v97, v97
	v_fmac_f32_e32 v175, v98, v98
	v_fmac_f32_e32 v175, v99, v99
	s_waitcnt vmcnt(17)
	v_fmac_f32_e32 v31, v100, v100
	v_fmac_f32_e32 v31, v101, v101
	v_fmac_f32_e32 v31, v102, v102
	v_fmac_f32_e32 v31, v103, v103
	s_waitcnt vmcnt(16)
	v_fmac_f32_e32 v175, v104, v104
	v_fmac_f32_e32 v175, v105, v105
	v_fmac_f32_e32 v175, v106, v106
	v_fmac_f32_e32 v175, v107, v107
	v_add_f32_e32 v31, v31, v175
	ds_bpermute_b32 v64, v66, v31
	s_waitcnt lgkmcnt(0)
	v_add_f32_e32 v31, v31, v64
	ds_bpermute_b32 v64, v67, v31
	s_waitcnt lgkmcnt(0)
	v_add_f32_e32 v31, v31, v64
	ds_bpermute_b32 v64, v68, v31
	s_waitcnt lgkmcnt(0)
	v_add_f32_e32 v31, v31, v64
	ds_bpermute_b32 v64, v69, v31
	s_waitcnt lgkmcnt(0)
	v_add_f32_e32 v31, v31, v64
	ds_bpermute_b32 v64, v70, v31
	s_waitcnt lgkmcnt(0)
	v_add_f32_e32 v31, v31, v64
	ds_bpermute_b32 v64, v71, v31
	s_waitcnt lgkmcnt(0)
	v_add_f32_e32 v31, v31, v64
	v_fmamk_f32 v31, v31, 0x3a000000, v65
	v_mul_f32_e32 v64, 0x4b800000, v31
	v_cmp_gt_f32_e32 vcc, s31, v31
	s_nop 1
	v_cndmask_b32_e32 v31, v31, v64, vcc
	v_rsq_f32_e32 v31, v31
	s_nop 0
	v_mul_f32_e32 v64, 0x45800000, v31
	v_cndmask_b32_e32 v64, v31, v64, vcc
	v_pk_mul_f32 v[76:77], v[76:77], v[64:65] op_sel_hi:[1,0]
	v_pk_mul_f32 v[78:79], v[78:79], v[64:65] op_sel_hi:[1,0]
	v_pk_mul_f32 v[76:77], v[112:113], v[76:77]
	v_pk_mul_f32 v[78:79], v[114:115], v[78:79]
	v_pk_add_f32 v[164:165], v[176:177], 1.0 op_sel_hi:[1,0]
	v_pk_add_f32 v[110:111], v[178:179], 1.0 op_sel_hi:[1,0]
	v_pk_fma_f32 v[76:77], v[164:165], v[76:77], v[208:209]
	v_pk_fma_f32 v[78:79], v[110:111], v[78:79], v[210:211]
	v_cvt_pk_bf16_f32 v76, v76, v77
	v_cvt_pk_bf16_f32 v77, v78, v79
	global_store_dwordx2 v[42:43], v[76:77], off
	v_pk_mul_f32 v[80:81], v[80:81], v[64:65] op_sel_hi:[1,0]
	v_pk_mul_f32 v[82:83], v[82:83], v[64:65] op_sel_hi:[1,0]
	v_pk_mul_f32 v[80:81], v[116:117], v[80:81]
	v_pk_mul_f32 v[82:83], v[118:119], v[82:83]
	v_pk_add_f32 v[164:165], v[180:181], 1.0 op_sel_hi:[1,0]
	v_pk_add_f32 v[110:111], v[182:183], 1.0 op_sel_hi:[1,0]
	v_pk_fma_f32 v[80:81], v[164:165], v[80:81], v[212:213]
	v_pk_fma_f32 v[82:83], v[110:111], v[82:83], v[214:215]
	v_cvt_pk_bf16_f32 v80, v80, v81
	v_cvt_pk_bf16_f32 v81, v82, v83
	global_store_dwordx2 v[42:43], v[80:81], off offset:512
	v_pk_mul_f32 v[84:85], v[84:85], v[64:65] op_sel_hi:[1,0]
	v_pk_mul_f32 v[86:87], v[86:87], v[64:65] op_sel_hi:[1,0]
	v_pk_mul_f32 v[84:85], v[120:121], v[84:85]
	v_pk_mul_f32 v[86:87], v[122:123], v[86:87]
	v_pk_add_f32 v[164:165], v[184:185], 1.0 op_sel_hi:[1,0]
	v_pk_add_f32 v[110:111], v[186:187], 1.0 op_sel_hi:[1,0]
	v_pk_fma_f32 v[84:85], v[164:165], v[84:85], v[216:217]
	v_pk_fma_f32 v[86:87], v[110:111], v[86:87], v[218:219]
	v_cvt_pk_bf16_f32 v84, v84, v85
	v_cvt_pk_bf16_f32 v85, v86, v87
	global_store_dwordx2 v[42:43], v[84:85], off offset:1024
	v_pk_mul_f32 v[88:89], v[88:89], v[64:65] op_sel_hi:[1,0]
	v_pk_mul_f32 v[90:91], v[90:91], v[64:65] op_sel_hi:[1,0]
	v_pk_mul_f32 v[88:89], v[124:125], v[88:89]
	v_pk_mul_f32 v[90:91], v[126:127], v[90:91]
	v_pk_add_f32 v[164:165], v[188:189], 1.0 op_sel_hi:[1,0]
	v_pk_add_f32 v[110:111], v[190:191], 1.0 op_sel_hi:[1,0]
	v_pk_fma_f32 v[88:89], v[164:165], v[88:89], v[220:221]
	v_pk_fma_f32 v[90:91], v[110:111], v[90:91], v[222:223]
	v_cvt_pk_bf16_f32 v88, v88, v89
	v_cvt_pk_bf16_f32 v89, v90, v91
	global_store_dwordx2 v[42:43], v[88:89], off offset:1536
	v_pk_mul_f32 v[92:93], v[92:93], v[64:65] op_sel_hi:[1,0]
	v_pk_mul_f32 v[94:95], v[94:95], v[64:65] op_sel_hi:[1,0]
	v_pk_mul_f32 v[92:93], v[128:129], v[92:93]
	v_pk_mul_f32 v[94:95], v[130:131], v[94:95]
	v_pk_add_f32 v[164:165], v[192:193], 1.0 op_sel_hi:[1,0]
	v_pk_add_f32 v[110:111], v[194:195], 1.0 op_sel_hi:[1,0]
	v_pk_fma_f32 v[92:93], v[164:165], v[92:93], v[224:225]
	v_pk_fma_f32 v[94:95], v[110:111], v[94:95], v[226:227]
	v_cvt_pk_bf16_f32 v92, v92, v93
	v_cvt_pk_bf16_f32 v93, v94, v95
	global_store_dwordx2 v[42:43], v[92:93], off offset:2048
	v_pk_mul_f32 v[96:97], v[96:97], v[64:65] op_sel_hi:[1,0]
	v_pk_mul_f32 v[98:99], v[98:99], v[64:65] op_sel_hi:[1,0]
	v_pk_mul_f32 v[96:97], v[132:133], v[96:97]
	v_pk_mul_f32 v[98:99], v[134:135], v[98:99]
	v_pk_add_f32 v[164:165], v[196:197], 1.0 op_sel_hi:[1,0]
	v_pk_add_f32 v[110:111], v[198:199], 1.0 op_sel_hi:[1,0]
	v_pk_fma_f32 v[96:97], v[164:165], v[96:97], v[228:229]
	v_pk_fma_f32 v[98:99], v[110:111], v[98:99], v[230:231]
	v_cvt_pk_bf16_f32 v96, v96, v97
	v_cvt_pk_bf16_f32 v97, v98, v99
	global_store_dwordx2 v[42:43], v[96:97], off offset:2560
	v_pk_mul_f32 v[100:101], v[100:101], v[64:65] op_sel_hi:[1,0]
	v_pk_mul_f32 v[102:103], v[102:103], v[64:65] op_sel_hi:[1,0]
	v_pk_mul_f32 v[100:101], v[136:137], v[100:101]
	v_pk_mul_f32 v[102:103], v[138:139], v[102:103]
	v_pk_add_f32 v[164:165], v[200:201], 1.0 op_sel_hi:[1,0]
	v_pk_add_f32 v[110:111], v[202:203], 1.0 op_sel_hi:[1,0]
	v_pk_fma_f32 v[100:101], v[164:165], v[100:101], v[144:145]
	v_pk_fma_f32 v[102:103], v[110:111], v[102:103], v[146:147]
	v_cvt_pk_bf16_f32 v100, v100, v101
	v_cvt_pk_bf16_f32 v101, v102, v103
	global_store_dwordx2 v[42:43], v[100:101], off offset:3072
	v_pk_mul_f32 v[104:105], v[104:105], v[64:65] op_sel_hi:[1,0]
	v_pk_mul_f32 v[106:107], v[106:107], v[64:65] op_sel_hi:[1,0]
	v_pk_mul_f32 v[104:105], v[140:141], v[104:105]
	v_pk_mul_f32 v[106:107], v[142:143], v[106:107]
	v_pk_add_f32 v[164:165], v[204:205], 1.0 op_sel_hi:[1,0]
	v_pk_add_f32 v[110:111], v[206:207], 1.0 op_sel_hi:[1,0]
	v_pk_fma_f32 v[104:105], v[164:165], v[104:105], v[148:149]
	v_pk_fma_f32 v[106:107], v[110:111], v[106:107], v[150:151]
	v_cvt_pk_bf16_f32 v104, v104, v105
	v_cvt_pk_bf16_f32 v105, v106, v107
	global_store_dwordx2 v[42:43], v[104:105], off offset:3584
	v_lshl_add_u64 v[42:43], v[42:43], 0, s[50:51]
	s_or_b64 s[8:9], s[100:101], s[8:9]
	s_andn2_b64 exec, exec, s[8:9]
	s_cbranch_execz .LBB0_1895
	s_branch .LBB0_1898
